# half the WGs run S5 pass A before the early conversion pass (HBM-bound early pass beside latency-bound pass A)
# speedup vs baseline: 1.0040x; 1.0040x over previous
.LBB0_15:
	s_load_dwordx4 s[4:7], s[86:87], 0x120
	s_lshr_b32 s85, s88, 6
	s_mul_i32 s97, s85, s94
	v_writelane_b32 v255, s0, 7
	s_add_i32 s0, s97, s2
	s_lshl_b32 s50, s94, 3
	v_writelane_b32 v255, s0, 8
	s_waitcnt lgkmcnt(0)
	s_cmp_lt_i32 s4, 1
	v_and_b32_e32 v244, 63, v0
	v_writelane_b32 v255, s1, 9
	s_cselect_b64 s[0:1], -1, 0
	s_cmp_gt_i32 s5, 0
	s_cselect_b64 s[4:5], -1, 0
	s_and_b64 s[0:1], s[0:1], s[4:5]
	s_andn2_b64 vcc, exec, s[0:1]
	s_cbranch_vccnz .LBB0_193
	s_mov_b32 s99, 1
	s_mov_b32 s101, 0
	s_bitcmp1_b32 s2, 3
	s_cbranch_scc1 .LBB0_193

.Lp0_skip_p:
	s_waitcnt lgkmcnt(0)
	s_barrier
	s_cmp_eq_u32 s99, 1
	s_cbranch_scc0 .Lp0_late_ret
	s_cmp_eq_u32 s101, 1
	s_cbranch_scc1 .Lp1_done
	s_branch .LBB0_193
.Lp0_late_ret:
	s_bitcmp1_b32 s2, 3
	s_cbranch_scc1 .Lp3_ret
	s_branch .Lp2_body

.LBB0_203:
	s_bitcmp1_b32 s2, 3
	s_cbranch_scc0 .Lp1_done
	s_mov_b32 s99, 1
	s_mov_b32 s101, 1
	s_waitcnt vmcnt(0) lgkmcnt(0)
	s_barrier
	s_branch .Lp0_body
